# banded attention units process two adjacent query tiles per wave sharing each K and V pair (half the K/V traffic per query)
# speedup vs baseline: 1.2229x; 1.0131x over previous
.LBB0_1161:
	s_andn2_b64 vcc, exec, s[0:1]
	s_cbranch_vccnz .LBB0_1273
	v_readlane_b32 s2, v254, 5
	v_readlane_b32 s3, v254, 6
	v_mov_b32_e32 v0, v208
	v_readlane_b32 s5, v254, 0
	s_load_dwordx4 s[40:43], s[2:3], 0xa0
	s_load_dword s4, s[2:3], 0xb0
	s_and_b32 s6, s5, -8
	v_ashrrev_i32_e32 v1, 6, v0
	v_mul_lo_u32 v2, v1, s46
	v_add_u32_e32 v1, s6, v1
	v_readlane_b32 s6, v254, 14
	v_add_u32_e32 v2, s5, v2
	v_readlane_b32 s7, v254, 15
	s_waitcnt lgkmcnt(0)
	s_mov_b64 s[0:1], s[42:43]
	v_cndmask_b32_e64 v49, v2, v1, s[6:7]
	v_readlane_b32 s6, v254, 16
	s_nop 1
	v_cmp_gt_i32_e32 vcc, s6, v49
	s_and_saveexec_b64 s[30:31], vcc
	s_cbranch_execz .LBB0_1215
	s_cmpk_lg_i32 s46, 0x100
	s_cbranch_scc1 .Lband_orig
	s_load_dwordx2 s[6:7], s[2:3], 0x30
	v_readlane_b32 s8, v254, 33
	s_and_b32 s56, s5, 7
	s_lshl_b32 s8, s8, 3
	s_add_i32 s8, s8, s56
	s_lshl_b32 s8, s8, 2
	s_waitcnt lgkmcnt(0)
	s_load_dword s9, s[6:7], s8
	v_lshrrev_b32_e32 v0, 6, v208
	s_waitcnt lgkmcnt(0)
	v_readfirstlane_b32 s1, v0
	s_lshr_b32 s7, s5, 3
	s_lshl_b32 s7, s7, 3
	s_add_i32 s7, s7, s1
	s_lshl_b32 s48, s1, 10
	s_mov_b32 s40, 0x3e38aa3b
	s_mov_b32 s41, 0x3e38aa3b
	s_mov_b32 s57, 0x20400
	s_mul_i32 s0, s1, 0x1200
	s_add_i32 s0, s0, 0x2000
	v_and_b32_e32 v100, 63, v208
	v_lshrrev_b32_e32 v101, 3, v100
	v_mul_u32_u24_e32 v101, 0x90, v101
	v_and_b32_e32 v102, 7, v100
	v_lshl_add_u32 v101, v102, 4, v101
	v_add_u32_e32 v114, s0, v101
	v_bfe_u32 v101, v208, 4, 2
	v_mul_u32_u24_e32 v101, 0x240, v101
	v_and_b32_e32 v102, 15, v208
	v_lshl_add_u32 v101, v102, 1, v101
	v_add_u32_e32 v115, s0, v101
	v_and_b32_e32 v116, 15, v208
	v_bfe_u32 v100, v208, 4, 2
	v_lshlrev_b32_e32 v117, 2, v100
	v_lshlrev_b32_e32 v118, 3, v100
	v_cmp_eq_u32_e32 vcc, 0, v100
	s_nop 1
	v_cndmask_b32_e64 v120, 0, 1.0, vcc
	s_waitcnt lgkmcnt(0)
	v_mov_b32_e32 v119, s9
	v_mul_f32_e32 v119, 0x3fb8aa3b, v119
	s_mov_b32 s6, 0
	s_lshr_b32 s0, s6, 2
	s_cmp_eq_u32 s0, 0
	s_cselect_b32 s3, 1, 0
	s_add_i32 s1, s0, -1
	s_max_i32 s1, s1, 0
	s_lshl_b32 s13, s1, 1
	s_and_b32 s1, s6, 1
	s_lshl_b32 s1, s1, 8
	s_add_i32 s1, s1, s7
	s_lshl_b32 s1, s1, 1
	s_sub_i32 s2, 10, s13
	s_lshr_b32 s14, s1, s2
	s_lshr_b32 s2, 0x400, s13
	s_add_i32 s2, s2, -1
	s_and_b32 s1, s1, s2
	s_lshl_b32 s8, s1, 4
	s_add_i32 s12, s1, 1
	s_sub_i32 s2, 0x80, s3
	s_sub_i32 s2, s8, s2
	s_max_i32 s2, s2, 0
	s_lshr_b32 s2, s2, 4
	s_and_b32 s11, s2, -2
	s_sub_i32 s2, s12, s11
	s_lshr_b32 s2, s2, 1
	s_add_i32 s9, s2, 1
	s_bfe_u32 s2, s6, 0x10001
	s_mul_i32 s2, s2, 0x4800000
	s_mul_i32 s0, s14, 0x1200
	s_add_i32 s2, s2, s0
	s_add_i32 s2, s2, 0xcd00000
	s_add_u32 s86, s42, s2
	s_addc_u32 s87, s43, 0
	s_lshl_b32 s0, 0x12000, s13
	s_mul_i32 s15, s1, s0
	s_lshl_b32 s1, s56, 7
	s_lshr_b32 s2, s56, 2
	s_lshl_b32 s2, s2, 7
	s_cmp_eq_u32 s3, 1
	s_cselect_b32 s0, s2, s1
	s_mul_i32 s2, s3, 0x600
	s_sub_i32 s2, 0xa00, s2
	s_add_i32 s2, s2, s0
	s_add_u32 s24, s86, s2
	s_addc_u32 s25, s87, 0
	s_mul_i32 s2, s3, 0x900
	s_sub_i32 s2, 0xe00, s2
	s_add_i32 s2, s2, s0
	s_add_u32 s26, s86, s2
	s_addc_u32 s27, s87, 0
	s_mul_i32 s2, s3, 0x600
	s_sub_i32 s2, 0x600, s2
	s_add_i32 s2, s2, s1
	s_add_i32 s2, s2, s15
	s_add_u32 s62, s86, s2
	s_addc_u32 s63, s87, 0
	s_mov_b32 s10, 0
	v_lshlrev_b32_e32 v90, s13, v116
	v_mul_u32_u24_e32 v90, 0x1200, v90
	v_lshl_add_u32 v111, v118, 1, v90
	v_and_b32_e32 v90, 63, v208
	v_and_b32_e32 v123, 7, v90
	v_lshlrev_b32_e32 v123, 4, v123
	v_lshrrev_b32_e32 v90, 3, v90
	v_add_u32_e32 v91, 0, v90
	v_lshlrev_b32_e32 v91, s13, v91
	v_mul_u32_u24_e32 v91, 0x1200, v91
	v_add_u32_e32 v112, v91, v123
	v_add_u32_e32 v91, 8, v90
	v_lshlrev_b32_e32 v91, s13, v91
	v_mul_u32_u24_e32 v91, 0x1200, v91
	v_add_u32_e32 v113, v91, v123
	global_load_dwordx4 v[16:19], v111, s[62:63]
	global_load_dwordx4 v[20:23], v111, s[62:63] offset:64
	s_lshl_b32 s0, 0x12000, s13
	s_add_u32 s62, s62, s0
	s_addc_u32 s63, s63, 0
	global_load_dwordx4 v[160:163], v111, s[62:63]
	global_load_dwordx4 v[164:167], v111, s[62:63] offset:64
	s_lshl_b32 s1, 0x12000, s13
	s_mul_i32 s0, s11, s1
	s_add_u32 s16, s24, s0
	s_addc_u32 s17, s25, 0
	s_add_u32 s20, s26, s0
	s_addc_u32 s21, s27, 0
	s_add_i32 s2, s11, 1
	s_cmp_gt_i32 s2, s12
	s_cselect_b32 s2, s11, s2
	s_mul_i32 s0, s2, s1
	s_add_u32 s18, s24, s0
	s_addc_u32 s19, s25, 0
	s_add_u32 s22, s26, s0
	s_addc_u32 s23, s27, 0
	global_load_dwordx4 v[24:27], v111, s[16:17]
	global_load_dwordx4 v[28:31], v111, s[16:17] offset:64
	global_load_dwordx4 v[32:35], v111, s[18:19]
	global_load_dwordx4 v[36:39], v111, s[18:19] offset:64
	global_load_dwordx4 v[40:43], v112, s[20:21]
	global_load_dwordx4 v[44:47], v113, s[20:21]
	global_load_dwordx4 v[48:51], v112, s[22:23]
	global_load_dwordx4 v[52:55], v113, s[22:23]
	s_lshr_b32 s0, s6, 2
	s_cmp_eq_u32 s0, 0
	s_cselect_b32 s2, 1, 0
	s_cselect_b32 s3, 0, 8
	s_sub_i32 s2, 0x80, s2
	s_add_i32 s3, s3, s56
	v_and_b32_e32 v100, 63, v208
	v_lshlrev_b32_e32 v107, 2, v100
	v_add_u32_e32 v107, s48, v107
	v_add_u32_e32 v100, 0xffffffe0, v100
	v_mov_b32_e32 v106, 0xf149f2ca
	s_mov_b32 s0, 4
.Lb_lute:
	v_max_i32_e32 v101, 0, v100
	v_min_i32_e32 v101, 0xff, v101
	v_lshlrev_b32_e32 v101, s13, v101
	v_cvt_f32_u32_e32 v102, v101
	v_mul_f32_e32 v102, 0x3d800000, v102
	v_log_f32_e32 v102, v102
	s_nop 0
	v_mul_f32_e32 v102, 0x40124925, v102
	v_cvt_i32_f32_e32 v102, v102
	v_med3_i32 v102, v102, 0, 15
	v_add_u32_e32 v102, 16, v102
	v_cmp_gt_u32_e32 vcc, 16, v101
	s_nop 1
	v_cndmask_b32_e32 v102, v102, v101, vcc
	v_lshl_add_u32 v102, v102, 4, s3
	v_lshl_add_u32 v102, v102, 2, s57
	ds_read_b32 v102, v102
	v_cmp_ge_u32_e32 vcc, s2, v100
	s_waitcnt lgkmcnt(0)
	v_mul_f32_e32 v102, 0x3fb8aa3b, v102
	v_cndmask_b32_e32 v102, v106, v102, vcc
	ds_write_b32 v107, v102
	v_add_u32_e32 v100, 64, v100
	v_add_u32_e32 v107, 0x100, v107
	s_add_i32 s0, s0, -1
	s_cmp_lg_u32 s0, 0
	s_cbranch_scc1 .Lb_lute
	s_waitcnt lgkmcnt(0)
	s_lshl_b32 s0, s11, 4
	s_sub_i32 s0, s8, s0
	s_add_i32 s0, s0, 13
	s_lshl_b32 s0, s0, 2
	s_add_i32 s0, s0, s48
	v_sub_u32_e32 v110, v116, v117
	v_lshl_add_u32 v110, v110, 2, s0
	s_lshr_b32 s0, s6, 2
	s_cmp_eq_u32 s0, 0
	s_cselect_b64 vcc, -1, 0
	v_mov_b32_e32 v90, 0xefa18f08
	s_nop 1
	v_cndmask_b32_e32 v108, v90, v119, vcc
	v_cndmask_b32_e32 v109, 0, v120, vcc
	v_cndmask_b32_e32 v168, v90, v119, vcc
	v_cndmask_b32_e32 v169, 0, v120, vcc
	v_mov_b32_e32 v0, 0
	v_mov_b32_e32 v1, 0
	v_mov_b32_e32 v2, 0
	v_mov_b32_e32 v3, 0
	v_mov_b32_e32 v4, 0
	v_mov_b32_e32 v5, 0
	v_mov_b32_e32 v6, 0
	v_mov_b32_e32 v7, 0
	v_mov_b32_e32 v8, 0
	v_mov_b32_e32 v9, 0
	v_mov_b32_e32 v10, 0
	v_mov_b32_e32 v11, 0
	v_mov_b32_e32 v12, 0
	v_mov_b32_e32 v13, 0
	v_mov_b32_e32 v14, 0
	v_mov_b32_e32 v15, 0
	v_mov_b32_e32 v144, 0
	v_mov_b32_e32 v145, 0
	v_mov_b32_e32 v146, 0
	v_mov_b32_e32 v147, 0
	v_mov_b32_e32 v148, 0
	v_mov_b32_e32 v149, 0
	v_mov_b32_e32 v150, 0
	v_mov_b32_e32 v151, 0
	v_mov_b32_e32 v152, 0
	v_mov_b32_e32 v153, 0
	v_mov_b32_e32 v154, 0
	v_mov_b32_e32 v155, 0
	v_mov_b32_e32 v156, 0
	v_mov_b32_e32 v157, 0
	v_mov_b32_e32 v158, 0
	v_mov_b32_e32 v159, 0
.Lb_step:
	s_waitcnt vmcnt(0)
	ds_write_b128 v114, v[40:43] offset:0
	ds_write_b128 v114, v[44:47] offset:1152
	ds_write_b128 v114, v[48:51] offset:2304
	ds_write_b128 v114, v[52:55] offset:3456
	ds_read_b32 v100, v110 offset:76
	ds_read_b32 v101, v110 offset:72
	ds_read_b32 v102, v110 offset:68
	ds_read_b32 v103, v110 offset:64
	ds_read_b32 v104, v110 offset:12
	ds_read_b32 v105, v110 offset:8
	ds_read_b32 v106, v110 offset:4
	ds_read_b32 v107, v110 offset:0
	ds_read_b32 v124, v110 offset:140
	ds_read_b32 v125, v110 offset:136
	ds_read_b32 v126, v110 offset:132
	ds_read_b32 v127, v110 offset:128
	ds_read_b32 v128, v110 offset:76
	ds_read_b32 v129, v110 offset:72
	ds_read_b32 v130, v110 offset:68
	ds_read_b32 v131, v110 offset:64
	v_add_u32_e32 v110, 0xffffff80, v110
	v_mfma_f32_16x16x32_bf16 v[92:95], v[24:27], v[16:19], 0
	v_mfma_f32_16x16x32_bf16 v[96:99], v[32:35], v[16:19], 0
	v_mfma_f32_16x16x32_bf16 v[132:135], v[24:27], v[160:163], 0
	v_mfma_f32_16x16x32_bf16 v[136:139], v[32:35], v[160:163], 0
	v_mfma_f32_16x16x32_bf16 v[92:95], v[28:31], v[20:23], v[92:95]
	v_mfma_f32_16x16x32_bf16 v[96:99], v[36:39], v[20:23], v[96:99]
	v_mfma_f32_16x16x32_bf16 v[132:135], v[28:31], v[164:167], v[132:135]
	v_mfma_f32_16x16x32_bf16 v[136:139], v[36:39], v[164:167], v[136:139]
	s_add_i32 s1, s10, 1
	s_cmp_ge_i32 s1, s9
	s_cbranch_scc1 .Lb_last
	s_mov_b32 s49, 0
	s_add_i32 s3, s11, 2
	s_lshl_b32 s1, 0x12000, s13
	s_mul_i32 s0, s3, s1
	s_add_u32 s16, s24, s0
	s_addc_u32 s17, s25, 0
	s_add_u32 s20, s26, s0
	s_addc_u32 s21, s27, 0
	s_add_i32 s2, s3, 1
	s_cmp_gt_i32 s2, s12
	s_cselect_b32 s2, s3, s2
	s_mul_i32 s0, s2, s1
	s_add_u32 s18, s24, s0
	s_addc_u32 s19, s25, 0
	s_add_u32 s22, s26, s0
	s_addc_u32 s23, s27, 0
	global_load_dwordx4 v[24:27], v111, s[16:17]
	global_load_dwordx4 v[28:31], v111, s[16:17] offset:64
	global_load_dwordx4 v[32:35], v111, s[18:19]
	global_load_dwordx4 v[36:39], v111, s[18:19] offset:64
	global_load_dwordx4 v[40:43], v112, s[20:21]
	global_load_dwordx4 v[44:47], v113, s[20:21]
	global_load_dwordx4 v[48:51], v112, s[22:23]
	global_load_dwordx4 v[52:55], v113, s[22:23]
	s_branch .Lb_compute
.Lb_last:
	s_mov_b32 s49, 1
	s_add_i32 s0, s6, 1
	s_min_i32 s0, s0, 15
	s_mov_b32 s15, s0
	s_lshr_b32 s0, s15, 2
	s_cmp_eq_u32 s0, 0
	s_cselect_b32 s3, 1, 0
	s_add_i32 s1, s0, -1
	s_max_i32 s1, s1, 0
	s_lshl_b32 s38, s1, 1
	s_and_b32 s1, s15, 1
	s_lshl_b32 s1, s1, 8
	s_add_i32 s1, s1, s7
	s_lshl_b32 s1, s1, 1
	s_sub_i32 s2, 10, s38
	s_lshr_b32 s39, s1, s2
	s_lshr_b32 s2, 0x400, s38
	s_add_i32 s2, s2, -1
	s_and_b32 s1, s1, s2
	s_lshl_b32 s34, s1, 4
	s_add_i32 s37, s1, 1
	s_sub_i32 s2, 0x80, s3
	s_sub_i32 s2, s34, s2
	s_max_i32 s2, s2, 0
	s_lshr_b32 s2, s2, 4
	s_and_b32 s36, s2, -2
	s_sub_i32 s2, s37, s36
	s_lshr_b32 s2, s2, 1
	s_add_i32 s35, s2, 1
	s_bfe_u32 s2, s15, 0x10001
	s_mul_i32 s2, s2, 0x4800000
	s_mul_i32 s0, s39, 0x1200
	s_add_i32 s2, s2, s0
	s_add_i32 s2, s2, 0xcd00000
	s_add_u32 s86, s42, s2
	s_addc_u32 s87, s43, 0
	s_lshl_b32 s0, 0x12000, s38
	s_mul_i32 s15, s1, s0
	s_lshl_b32 s1, s56, 7
	s_lshr_b32 s2, s56, 2
	s_lshl_b32 s2, s2, 7
	s_cmp_eq_u32 s3, 1
	s_cselect_b32 s0, s2, s1
	s_mul_i32 s2, s3, 0x600
	s_sub_i32 s2, 0xa00, s2
	s_add_i32 s2, s2, s0
	s_add_u32 s24, s86, s2
	s_addc_u32 s25, s87, 0
	s_mul_i32 s2, s3, 0x900
	s_sub_i32 s2, 0xe00, s2
	s_add_i32 s2, s2, s0
	s_add_u32 s26, s86, s2
	s_addc_u32 s27, s87, 0
	s_mul_i32 s2, s3, 0x600
	s_sub_i32 s2, 0x600, s2
	s_add_i32 s2, s2, s1
	s_add_i32 s2, s2, s15
	s_add_u32 s62, s86, s2
	s_addc_u32 s63, s87, 0
	v_lshlrev_b32_e32 v90, s38, v116
	v_mul_u32_u24_e32 v90, 0x1200, v90
	v_lshl_add_u32 v111, v118, 1, v90
	v_and_b32_e32 v90, 63, v208
	v_and_b32_e32 v123, 7, v90
	v_lshlrev_b32_e32 v123, 4, v123
	v_lshrrev_b32_e32 v90, 3, v90
	v_add_u32_e32 v91, 0, v90
	v_lshlrev_b32_e32 v91, s38, v91
	v_mul_u32_u24_e32 v91, 0x1200, v91
	v_add_u32_e32 v112, v91, v123
	v_add_u32_e32 v91, 8, v90
	v_lshlrev_b32_e32 v91, s38, v91
	v_mul_u32_u24_e32 v91, 0x1200, v91
	v_add_u32_e32 v113, v91, v123
	s_lshl_b32 s1, 0x12000, s38
	s_mul_i32 s0, s36, s1
	s_add_u32 s16, s24, s0
	s_addc_u32 s17, s25, 0
	s_add_u32 s20, s26, s0
	s_addc_u32 s21, s27, 0
	s_add_i32 s2, s36, 1
	s_cmp_gt_i32 s2, s37
	s_cselect_b32 s2, s36, s2
	s_mul_i32 s0, s2, s1
	s_add_u32 s18, s24, s0
	s_addc_u32 s19, s25, 0
	s_add_u32 s22, s26, s0
	s_addc_u32 s23, s27, 0
	global_load_dwordx4 v[24:27], v111, s[16:17]
	global_load_dwordx4 v[28:31], v111, s[16:17] offset:64
	global_load_dwordx4 v[32:35], v111, s[18:19]
	global_load_dwordx4 v[36:39], v111, s[18:19] offset:64
	global_load_dwordx4 v[40:43], v112, s[20:21]
	global_load_dwordx4 v[44:47], v113, s[20:21]
	global_load_dwordx4 v[48:51], v112, s[22:23]
	global_load_dwordx4 v[52:55], v113, s[22:23]
	global_load_dwordx4 v[16:19], v111, s[62:63]
	global_load_dwordx4 v[20:23], v111, s[62:63] offset:64
	s_lshl_b32 s0, 0x12000, s38
	s_add_u32 s62, s62, s0
	s_addc_u32 s63, s63, 0
	global_load_dwordx4 v[160:163], v111, s[62:63]
	global_load_dwordx4 v[164:167], v111, s[62:63] offset:64
.Lb_compute:
	s_waitcnt lgkmcnt(0)
	ds_read_u16 v56, v115 offset:0
	ds_read_u16 v74, v115 offset:144
	ds_read_u16 v57, v115 offset:288
	ds_read_u16 v75, v115 offset:432
	ds_read_u16 v60, v115 offset:32
	ds_read_u16 v78, v115 offset:176
	ds_read_u16 v61, v115 offset:320
	ds_read_u16 v79, v115 offset:464
	ds_read_u16 v66, v115 offset:64
	ds_read_u16 v82, v115 offset:208
	ds_read_u16 v67, v115 offset:352
	ds_read_u16 v83, v115 offset:496
	ds_read_u16 v70, v115 offset:96
	ds_read_u16 v86, v115 offset:240
	ds_read_u16 v71, v115 offset:384
	ds_read_u16 v87, v115 offset:528
	ds_read_u16 v58, v115 offset:2304
	ds_read_u16 v76, v115 offset:2448
	ds_read_u16 v59, v115 offset:2592
	ds_read_u16 v77, v115 offset:2736
	ds_read_u16 v62, v115 offset:2336
	ds_read_u16 v80, v115 offset:2480
	ds_read_u16 v63, v115 offset:2624
	ds_read_u16 v81, v115 offset:2768
	ds_read_u16 v68, v115 offset:2368
	ds_read_u16 v84, v115 offset:2512
	ds_read_u16 v69, v115 offset:2656
	ds_read_u16 v85, v115 offset:2800
	ds_read_u16 v72, v115 offset:2400
	ds_read_u16 v88, v115 offset:2544
	ds_read_u16 v73, v115 offset:2688
	ds_read_u16 v89, v115 offset:2832
	v_pk_fma_f32 v[92:93], v[92:93], s[40:41], v[100:101] op_sel_hi:[1,0,1]
	v_pk_fma_f32 v[94:95], v[94:95], s[40:41], v[102:103] op_sel_hi:[1,0,1]
	v_pk_fma_f32 v[96:97], v[96:97], s[40:41], v[104:105] op_sel_hi:[1,0,1]
	v_pk_fma_f32 v[98:99], v[98:99], s[40:41], v[106:107] op_sel_hi:[1,0,1]
	v_max3_f32 v100, v92, v93, v94
	v_max3_f32 v101, v95, v96, v97
	v_max3_f32 v100, v100, v98, v99
	v_max_f32_e32 v100, v100, v101
	v_mov_b32_e32 v101, v100
	s_nop 1
	v_permlane16_swap_b32_e32 v101, v100
	v_max_f32_e32 v100, v100, v101
	v_mov_b32_e32 v101, v100
	s_nop 1
	v_permlane32_swap_b32_e32 v101, v100
	v_max_f32_e32 v102, v100, v101
	v_cmp_gt_f32_e32 vcc, v102, v108
	s_cbranch_vccz .Lb_norescA
	v_max_f32_e32 v102, v108, v102
	v_sub_f32_e32 v100, v108, v102
	v_exp_f32_e32 v100, v100
	v_mov_b32_e32 v108, v102
	s_nop 0
	v_pk_mul_f32 v[0:1], v[0:1], v[100:101] op_sel_hi:[1,0]
	v_pk_mul_f32 v[2:3], v[2:3], v[100:101] op_sel_hi:[1,0]
	v_pk_mul_f32 v[4:5], v[4:5], v[100:101] op_sel_hi:[1,0]
	v_pk_mul_f32 v[6:7], v[6:7], v[100:101] op_sel_hi:[1,0]
	v_pk_mul_f32 v[8:9], v[8:9], v[100:101] op_sel_hi:[1,0]
	v_pk_mul_f32 v[10:11], v[10:11], v[100:101] op_sel_hi:[1,0]
	v_pk_mul_f32 v[12:13], v[12:13], v[100:101] op_sel_hi:[1,0]
	v_pk_mul_f32 v[14:15], v[14:15], v[100:101] op_sel_hi:[1,0]
	v_mul_f32_e32 v109, v109, v100
.Lb_norescA:
	v_pk_add_f32 v[92:93], v[92:93], v[108:109] op_sel_hi:[1,0] neg_lo:[0,1] neg_hi:[0,1]
	v_pk_add_f32 v[94:95], v[94:95], v[108:109] op_sel_hi:[1,0] neg_lo:[0,1] neg_hi:[0,1]
	v_pk_add_f32 v[96:97], v[96:97], v[108:109] op_sel_hi:[1,0] neg_lo:[0,1] neg_hi:[0,1]
	v_pk_add_f32 v[98:99], v[98:99], v[108:109] op_sel_hi:[1,0] neg_lo:[0,1] neg_hi:[0,1]
	v_exp_f32_e32 v92, v92
	v_exp_f32_e32 v93, v93
	v_exp_f32_e32 v94, v94
	v_exp_f32_e32 v95, v95
	v_exp_f32_e32 v96, v96
	v_exp_f32_e32 v97, v97
	v_exp_f32_e32 v98, v98
	v_exp_f32_e32 v99, v99
	s_nop 0
	v_pk_add_f32 v[100:101], v[92:93], v[94:95]
	v_pk_add_f32 v[100:101], v[100:101], v[96:97]
	v_pk_add_f32 v[100:101], v[100:101], v[98:99]
	v_add_f32_e32 v100, v100, v101
	v_add_f32_e32 v109, v109, v100
	v_cvt_pk_bf16_f32 v92, v92, v93
	v_cvt_pk_bf16_f32 v93, v94, v95
	v_cvt_pk_bf16_f32 v94, v96, v97
	v_cvt_pk_bf16_f32 v95, v98, v99
	v_pk_fma_f32 v[132:133], v[132:133], s[40:41], v[124:125] op_sel_hi:[1,0,1]
	v_pk_fma_f32 v[134:135], v[134:135], s[40:41], v[126:127] op_sel_hi:[1,0,1]
	v_pk_fma_f32 v[136:137], v[136:137], s[40:41], v[128:129] op_sel_hi:[1,0,1]
	v_pk_fma_f32 v[138:139], v[138:139], s[40:41], v[130:131] op_sel_hi:[1,0,1]
	v_max3_f32 v124, v132, v133, v134
	v_max3_f32 v125, v135, v136, v137
	v_max3_f32 v124, v124, v138, v139
	v_max_f32_e32 v124, v124, v125
	v_mov_b32_e32 v125, v124
	s_nop 1
	v_permlane16_swap_b32_e32 v125, v124
	v_max_f32_e32 v124, v124, v125
	v_mov_b32_e32 v125, v124
	s_nop 1
	v_permlane32_swap_b32_e32 v125, v124
	v_max_f32_e32 v126, v124, v125
	v_cmp_gt_f32_e32 vcc, v126, v168
	s_cbranch_vccz .Lb_norescB
	v_max_f32_e32 v126, v168, v126
	v_sub_f32_e32 v124, v168, v126
	v_exp_f32_e32 v124, v124
	v_mov_b32_e32 v168, v126
	s_nop 0
	v_pk_mul_f32 v[144:145], v[144:145], v[124:125] op_sel_hi:[1,0]
	v_pk_mul_f32 v[146:147], v[146:147], v[124:125] op_sel_hi:[1,0]
	v_pk_mul_f32 v[148:149], v[148:149], v[124:125] op_sel_hi:[1,0]
	v_pk_mul_f32 v[150:151], v[150:151], v[124:125] op_sel_hi:[1,0]
	v_pk_mul_f32 v[152:153], v[152:153], v[124:125] op_sel_hi:[1,0]
	v_pk_mul_f32 v[154:155], v[154:155], v[124:125] op_sel_hi:[1,0]
	v_pk_mul_f32 v[156:157], v[156:157], v[124:125] op_sel_hi:[1,0]
	v_pk_mul_f32 v[158:159], v[158:159], v[124:125] op_sel_hi:[1,0]
	v_mul_f32_e32 v169, v169, v124
.Lb_norescB:
	v_pk_add_f32 v[132:133], v[132:133], v[168:169] op_sel_hi:[1,0] neg_lo:[0,1] neg_hi:[0,1]
	v_pk_add_f32 v[134:135], v[134:135], v[168:169] op_sel_hi:[1,0] neg_lo:[0,1] neg_hi:[0,1]
	v_pk_add_f32 v[136:137], v[136:137], v[168:169] op_sel_hi:[1,0] neg_lo:[0,1] neg_hi:[0,1]
	v_pk_add_f32 v[138:139], v[138:139], v[168:169] op_sel_hi:[1,0] neg_lo:[0,1] neg_hi:[0,1]
	v_exp_f32_e32 v132, v132
	v_exp_f32_e32 v133, v133
	v_exp_f32_e32 v134, v134
	v_exp_f32_e32 v135, v135
	v_exp_f32_e32 v136, v136
	v_exp_f32_e32 v137, v137
	v_exp_f32_e32 v138, v138
	v_exp_f32_e32 v139, v139
	s_nop 0
	v_pk_add_f32 v[124:125], v[132:133], v[134:135]
	v_pk_add_f32 v[124:125], v[124:125], v[136:137]
	v_pk_add_f32 v[124:125], v[124:125], v[138:139]
	v_add_f32_e32 v124, v124, v125
	v_add_f32_e32 v169, v169, v124
	v_cvt_pk_bf16_f32 v132, v132, v133
	v_cvt_pk_bf16_f32 v133, v134, v135
	v_cvt_pk_bf16_f32 v134, v136, v137
	v_cvt_pk_bf16_f32 v135, v138, v139
	s_waitcnt lgkmcnt(0)
	v_lshl_or_b32 v56, v74, 16, v56
	v_lshl_or_b32 v57, v75, 16, v57
	v_lshl_or_b32 v58, v76, 16, v58
	v_lshl_or_b32 v59, v77, 16, v59
	v_lshl_or_b32 v60, v78, 16, v60
	v_lshl_or_b32 v61, v79, 16, v61
	v_lshl_or_b32 v62, v80, 16, v62
	v_lshl_or_b32 v63, v81, 16, v63
	v_lshl_or_b32 v66, v82, 16, v66
	v_lshl_or_b32 v67, v83, 16, v67
	v_lshl_or_b32 v68, v84, 16, v68
	v_lshl_or_b32 v69, v85, 16, v69
	v_lshl_or_b32 v70, v86, 16, v70
	v_lshl_or_b32 v71, v87, 16, v71
	v_lshl_or_b32 v72, v88, 16, v72
	v_lshl_or_b32 v73, v89, 16, v73
	s_nop 1
	v_mfma_f32_16x16x32_bf16 v[0:3], v[56:59], v[92:95], v[0:3]
	v_mfma_f32_16x16x32_bf16 v[144:147], v[56:59], v[132:135], v[144:147]
	v_mfma_f32_16x16x32_bf16 v[4:7], v[60:63], v[92:95], v[4:7]
	v_mfma_f32_16x16x32_bf16 v[148:151], v[60:63], v[132:135], v[148:151]
	v_mfma_f32_16x16x32_bf16 v[8:11], v[66:69], v[92:95], v[8:11]
	v_mfma_f32_16x16x32_bf16 v[152:155], v[66:69], v[132:135], v[152:155]
	v_mfma_f32_16x16x32_bf16 v[12:15], v[70:73], v[92:95], v[12:15]
	v_mfma_f32_16x16x32_bf16 v[156:159], v[70:73], v[132:135], v[156:159]
	s_cmp_eq_u32 s49, 0
	s_cbranch_scc0 .Lb_epilogue
	s_add_i32 s10, s10, 1
	s_add_i32 s11, s11, 2
	s_branch .Lb_step
.Lb_epilogue:
	s_nop 7
	v_mov_b32_e32 v100, v109
	s_nop 1
	v_permlane16_swap_b32_e32 v100, v109
	v_add_f32_e32 v109, v109, v100
	v_mov_b32_e32 v100, v109
	s_nop 1
	v_permlane32_swap_b32_e32 v100, v109
	v_add_f32_e32 v109, v109, v100
	v_rcp_f32_e32 v102, v109
	v_log_f32_e32 v103, v109
	s_nop 0
	v_pk_mul_f32 v[0:1], v[0:1], v[102:103] op_sel_hi:[1,0]
	v_pk_mul_f32 v[2:3], v[2:3], v[102:103] op_sel_hi:[1,0]
	v_pk_mul_f32 v[4:5], v[4:5], v[102:103] op_sel_hi:[1,0]
	v_pk_mul_f32 v[6:7], v[6:7], v[102:103] op_sel_hi:[1,0]
	v_pk_mul_f32 v[8:9], v[8:9], v[102:103] op_sel_hi:[1,0]
	v_pk_mul_f32 v[10:11], v[10:11], v[102:103] op_sel_hi:[1,0]
	v_pk_mul_f32 v[12:13], v[12:13], v[102:103] op_sel_hi:[1,0]
	v_pk_mul_f32 v[14:15], v[14:15], v[102:103] op_sel_hi:[1,0]
	v_add_f32_e32 v103, v103, v108
	v_mul_f32_e32 v103, 0x3f317218, v103
	s_add_i32 s0, s8, 0
	s_lshl_b32 s0, s0, s13
	s_add_i32 s0, s0, s14
	s_lshr_b32 s1, s6, 2
	s_bfe_u32 s2, s6, 0x10001
	s_cmp_eq_u32 s1, 0
	s_cbranch_scc1 .Lb_ep_mixerA
	s_add_i32 s1, s1, -1
	s_lshl_b32 s1, s1, 15
	s_lshl_b32 s2, s2, 14
	s_add_i32 s1, s1, s2
	s_add_i32 s1, s1, s0
	s_lshl_b32 s2, s1, 5
	s_lshl_b32 s3, s56, 2
	s_add_i32 s2, s2, s3
	s_add_i32 s2, s2, 0x1bd00000
	s_add_u32 s86, s42, s2
	s_addc_u32 s87, s43, 0
	v_lshlrev_b32_e32 v104, s13, v116
	v_lshlrev_b32_e32 v122, 5, v104
	s_mov_b64 exec, 0xffff
	global_store_dword v122, v103, s[86:87]
	s_mov_b64 exec, -1
	s_lshl_b32 s2, s1, 10
	s_lshl_b32 s3, s56, 7
	s_add_i32 s2, s2, s3
	s_add_i32 s2, s2, 0x15d00000
	s_add_u32 s86, s42, s2
	s_addc_u32 s87, s43, 0
	v_lshl_add_u32 v121, v104, 10, v118
	s_branch .Lb_ep_storeA

.Lb_ep_storeA:
	v_cvt_pk_bf16_f32 v0, v0, v1
	v_cvt_pk_bf16_f32 v1, v2, v3
	global_store_dwordx2 v121, v[0:1], s[86:87] offset:0
	v_cvt_pk_bf16_f32 v4, v4, v5
	v_cvt_pk_bf16_f32 v5, v6, v7
	global_store_dwordx2 v121, v[4:5], s[86:87] offset:32
	v_cvt_pk_bf16_f32 v8, v8, v9
	v_cvt_pk_bf16_f32 v9, v10, v11
	global_store_dwordx2 v121, v[8:9], s[86:87] offset:64
	v_cvt_pk_bf16_f32 v12, v12, v13
	v_cvt_pk_bf16_f32 v13, v14, v15
	global_store_dwordx2 v121, v[12:13], s[86:87] offset:96
	v_mov_b32_e32 v100, v169
	s_nop 1
	v_permlane16_swap_b32_e32 v100, v169
	v_add_f32_e32 v169, v169, v100
	v_mov_b32_e32 v100, v169
	s_nop 1
	v_permlane32_swap_b32_e32 v100, v169
	v_add_f32_e32 v169, v169, v100
	v_rcp_f32_e32 v102, v169
	v_log_f32_e32 v103, v169
	s_nop 0
	v_pk_mul_f32 v[144:145], v[144:145], v[102:103] op_sel_hi:[1,0]
	v_pk_mul_f32 v[146:147], v[146:147], v[102:103] op_sel_hi:[1,0]
	v_pk_mul_f32 v[148:149], v[148:149], v[102:103] op_sel_hi:[1,0]
	v_pk_mul_f32 v[150:151], v[150:151], v[102:103] op_sel_hi:[1,0]
	v_pk_mul_f32 v[152:153], v[152:153], v[102:103] op_sel_hi:[1,0]
	v_pk_mul_f32 v[154:155], v[154:155], v[102:103] op_sel_hi:[1,0]
	v_pk_mul_f32 v[156:157], v[156:157], v[102:103] op_sel_hi:[1,0]
	v_pk_mul_f32 v[158:159], v[158:159], v[102:103] op_sel_hi:[1,0]
	v_add_f32_e32 v103, v103, v168
	v_mul_f32_e32 v103, 0x3f317218, v103
	s_add_i32 s0, s8, 16
	s_lshl_b32 s0, s0, s13
	s_add_i32 s0, s0, s14
	s_lshr_b32 s1, s6, 2
	s_bfe_u32 s2, s6, 0x10001
	s_cmp_eq_u32 s1, 0
	s_cbranch_scc1 .Lb_ep_mixerB
	s_add_i32 s1, s1, -1
	s_lshl_b32 s1, s1, 15
	s_lshl_b32 s2, s2, 14
	s_add_i32 s1, s1, s2
	s_add_i32 s1, s1, s0
	s_lshl_b32 s2, s1, 5
	s_lshl_b32 s3, s56, 2
	s_add_i32 s2, s2, s3
	s_add_i32 s2, s2, 0x1bd00000
	s_add_u32 s86, s42, s2
	s_addc_u32 s87, s43, 0
	v_lshlrev_b32_e32 v104, s13, v116
	v_lshlrev_b32_e32 v122, 5, v104
	s_mov_b64 exec, 0xffff
	global_store_dword v122, v103, s[86:87]
	s_mov_b64 exec, -1
	s_lshl_b32 s2, s1, 10
	s_lshl_b32 s3, s56, 7
	s_add_i32 s2, s2, s3
	s_add_i32 s2, s2, 0x15d00000
	s_add_u32 s86, s42, s2
	s_addc_u32 s87, s43, 0
	v_lshl_add_u32 v121, v104, 10, v118
	s_branch .Lb_ep_storeB

.Lb_ep_storeB:
	v_cvt_pk_bf16_f32 v144, v144, v145
	v_cvt_pk_bf16_f32 v145, v146, v147
	global_store_dwordx2 v121, v[144:145], s[86:87] offset:0
	v_cvt_pk_bf16_f32 v148, v148, v149
	v_cvt_pk_bf16_f32 v149, v150, v151
	global_store_dwordx2 v121, v[148:149], s[86:87] offset:32
	v_cvt_pk_bf16_f32 v152, v152, v153
	v_cvt_pk_bf16_f32 v153, v154, v155
	global_store_dwordx2 v121, v[152:153], s[86:87] offset:64
	v_cvt_pk_bf16_f32 v156, v156, v157
	v_cvt_pk_bf16_f32 v157, v158, v159
	global_store_dwordx2 v121, v[156:157], s[86:87] offset:96
	s_add_i32 s0, s6, 1
	s_cmp_ge_i32 s0, 16
	s_cbranch_scc1 .Lb_exit
	s_lshr_b32 s1, s6, 2
	s_mov_b32 s6, s0
	s_mov_b32 s8, s34
	s_mov_b32 s9, s35
	s_mov_b32 s11, s36
	s_mov_b32 s12, s37
	s_mov_b32 s13, s38
	s_mov_b32 s14, s39
	s_mov_b32 s10, 0
	s_lshr_b32 s0, s6, 2
	s_cmp_eq_u32 s0, s1
	s_cbranch_scc1 .Lb_samekind
	s_lshr_b32 s0, s6, 2
	s_cmp_eq_u32 s0, 0
	s_cselect_b32 s2, 1, 0
	s_cselect_b32 s3, 0, 8
	s_sub_i32 s2, 0x80, s2
	s_add_i32 s3, s3, s56
	v_and_b32_e32 v100, 63, v208
	v_lshlrev_b32_e32 v107, 2, v100
	v_add_u32_e32 v107, s48, v107
	v_add_u32_e32 v100, 0xffffffe0, v100
	v_mov_b32_e32 v106, 0xf149f2ca
	s_mov_b32 s0, 4

.Lb_samekind:
	s_lshl_b32 s0, s11, 4
	s_sub_i32 s0, s8, s0
	s_add_i32 s0, s0, 13
	s_lshl_b32 s0, s0, 2
	s_add_i32 s0, s0, s48
	v_sub_u32_e32 v110, v116, v117
	v_lshl_add_u32 v110, v110, 2, s0
	s_lshr_b32 s0, s6, 2
	s_cmp_eq_u32 s0, 0
	s_cselect_b64 vcc, -1, 0
	v_mov_b32_e32 v90, 0xefa18f08
	s_nop 1
	v_cndmask_b32_e32 v108, v90, v119, vcc
	v_cndmask_b32_e32 v109, 0, v120, vcc
	v_cndmask_b32_e32 v168, v90, v119, vcc
	v_cndmask_b32_e32 v169, 0, v120, vcc
	v_mov_b32_e32 v0, 0
	v_mov_b32_e32 v1, 0
	v_mov_b32_e32 v2, 0
	v_mov_b32_e32 v3, 0
	v_mov_b32_e32 v4, 0
	v_mov_b32_e32 v5, 0
	v_mov_b32_e32 v6, 0
	v_mov_b32_e32 v7, 0
	v_mov_b32_e32 v8, 0
	v_mov_b32_e32 v9, 0
	v_mov_b32_e32 v10, 0
	v_mov_b32_e32 v11, 0
	v_mov_b32_e32 v12, 0
	v_mov_b32_e32 v13, 0
	v_mov_b32_e32 v14, 0
	v_mov_b32_e32 v15, 0
	v_mov_b32_e32 v144, 0
	v_mov_b32_e32 v145, 0
	v_mov_b32_e32 v146, 0
	v_mov_b32_e32 v147, 0
	v_mov_b32_e32 v148, 0
	v_mov_b32_e32 v149, 0
	v_mov_b32_e32 v150, 0
	v_mov_b32_e32 v151, 0
	v_mov_b32_e32 v152, 0
	v_mov_b32_e32 v153, 0
	v_mov_b32_e32 v154, 0
	v_mov_b32_e32 v155, 0
	v_mov_b32_e32 v156, 0
	v_mov_b32_e32 v157, 0
	v_mov_b32_e32 v158, 0
	v_mov_b32_e32 v159, 0
	s_branch .Lb_step
